# attention: per-query log-forget term enters through the QK^T MFMA's C operand (16 registers filled once per item) instead of 32 v_add_f32 per tile
# speedup vs baseline: 1.0189x; 1.0052x over previous
.LBB0_931:
	s_mov_b64 s[4:5], 0
	s_add_i32 s8, s3, 0xffffff80
	s_add_u32 s4, s96, s4
	s_addc_u32 s5, s97, s5
	s_and_b32 s9, s8, 0xff
	v_mov_b32_e32 v6, v176
	s_lshl_b32 s6, s9, 13
	s_add_u32 s6, s4, s6
	v_lshlrev_b32_e32 v4, 2, v6
	s_addc_u32 s7, s5, 0
	v_ashrrev_i32_e32 v5, 31, v4
	v_lshl_add_u64 v[0:1], v[4:5], 2, s[6:7]
	s_mov_b32 s6, 0x1a00000
	v_add_co_u32_e32 v0, vcc, s6, v0
	s_nop 1
	v_addc_co_u32_e32 v1, vcc, 0, v1, vcc
	s_barrier
	global_load_dwordx4 v[0:3], v[0:1], off
	v_cmp_lt_i32_e32 vcc, v181, v180
	s_waitcnt vmcnt(0)
	v_add_f32_e32 v1, v0, v1
	v_cndmask_b32_e32 v5, v181, v171, vcc
	v_add_f32_e32 v2, v2, v1
	v_lshlrev_b32_e32 v5, 2, v5
	v_add_f32_e32 v3, v3, v2
	ds_bpermute_b32 v5, v5, v3
	v_cmp_lt_i32_e32 vcc, v182, v180
	s_waitcnt lgkmcnt(0)
	v_add_f32_e32 v5, v3, v5
	v_cndmask_b32_e32 v7, v182, v171, vcc
	v_lshlrev_b32_e32 v8, 2, v7
	v_and_b32_e32 v7, 63, v6
	v_cmp_eq_u32_e32 vcc, 0, v7
	s_nop 1
	v_cndmask_b32_e32 v5, v5, v3, vcc
	ds_bpermute_b32 v8, v8, v5
	v_cmp_lt_i32_e32 vcc, v183, v180
	s_waitcnt lgkmcnt(0)
	v_add_f32_e32 v8, v5, v8
	v_cndmask_b32_e32 v9, v183, v171, vcc
	v_cmp_gt_u32_e32 vcc, 2, v7
	v_lshlrev_b32_e32 v9, 2, v9
	s_nop 0
	v_cndmask_b32_e32 v5, v8, v5, vcc
	ds_bpermute_b32 v8, v9, v5
	v_cmp_lt_i32_e32 vcc, v184, v180
	s_waitcnt lgkmcnt(0)
	v_add_f32_e32 v8, v5, v8
	v_cndmask_b32_e32 v9, v184, v171, vcc
	v_cmp_gt_u32_e32 vcc, 4, v7
	v_lshlrev_b32_e32 v9, 2, v9
	s_nop 0
	v_cndmask_b32_e32 v5, v8, v5, vcc
	ds_bpermute_b32 v8, v9, v5
	v_cmp_lt_i32_e32 vcc, v185, v180
	s_waitcnt lgkmcnt(0)
	v_add_f32_e32 v8, v5, v8
	v_cndmask_b32_e32 v9, v185, v171, vcc
	v_cmp_gt_u32_e32 vcc, 8, v7
	v_lshlrev_b32_e32 v9, 2, v9
	s_nop 0
	v_cndmask_b32_e32 v5, v8, v5, vcc
	ds_bpermute_b32 v8, v9, v5
	v_cmp_lt_i32_e32 vcc, v186, v180
	s_waitcnt lgkmcnt(0)
	v_add_f32_e32 v8, v5, v8
	v_cndmask_b32_e32 v9, v186, v171, vcc
	v_cmp_gt_u32_e32 vcc, 16, v7
	v_lshlrev_b32_e32 v9, 2, v9
	s_nop 0
	v_cndmask_b32_e32 v8, v8, v5, vcc
	ds_bpermute_b32 v9, v9, v8
	v_ashrrev_i32_e32 v5, 6, v6
	v_cmp_eq_u32_e32 vcc, 63, v7
	s_waitcnt lgkmcnt(0)
	v_add_f32_e32 v9, v8, v9
	s_and_saveexec_b64 s[6:7], vcc
	v_lshlrev_b32_e32 v10, 2, v5
	ds_write_b32 v10, v9 offset:26624
	s_or_b64 exec, exec, s[6:7]
	v_cmp_gt_u32_e32 vcc, 32, v7
	v_lshrrev_b32_e32 v16, 5, v7
	s_waitcnt lgkmcnt(0)
	v_cndmask_b32_e32 v7, v9, v8, vcc
	s_barrier
	ds_read_b128 v[8:11], v137 offset:26624
	ds_read_b128 v[12:15], v137 offset:26640
	v_cmp_lt_i32_e32 vcc, 0, v5
	v_sub_f32_e32 v7, v7, v3
	s_andn2_b32 s6, 0x700, s8
	s_waitcnt lgkmcnt(1)
	v_cndmask_b32_e32 v8, 0, v8, vcc
	v_cmp_lt_i32_e32 vcc, 1, v5
	v_add_f32_e32 v7, v7, v8
	v_and_b32_e32 v17, 31, v6
	v_cndmask_b32_e32 v8, 0, v9, vcc
	v_cmp_lt_i32_e32 vcc, 2, v5
	v_add_f32_e32 v7, v7, v8
	v_lshlrev_b32_e32 v4, 2, v4
	v_cndmask_b32_e32 v8, 0, v10, vcc
	v_cmp_lt_i32_e32 vcc, 3, v5
	v_add_f32_e32 v7, v7, v8
	v_lshlrev_b32_e32 v136, 4, v16
	v_cndmask_b32_e32 v8, 0, v11, vcc
	v_cmp_lt_i32_e32 vcc, 4, v5
	v_add_f32_e32 v7, v7, v8
	v_mov_b32_e32 v100, 0
	s_waitcnt lgkmcnt(0)
	v_cndmask_b32_e32 v8, 0, v12, vcc
	v_cmp_lt_i32_e32 vcc, 5, v5
	v_add_f32_e32 v7, v7, v8
	v_lshl_add_u32 v12, v5, 5, s6
	v_cndmask_b32_e32 v8, 0, v13, vcc
	v_cmp_lt_i32_e32 vcc, 6, v5
	v_add_f32_e32 v7, v7, v8
	s_lshl_b32 s6, s8, 8
	v_cndmask_b32_e32 v8, 0, v14, vcc
	v_cmp_lt_i32_e32 vcc, 7, v5
	v_add_f32_e32 v7, v7, v8
	v_or_b32_e32 v96, v12, v17
	v_cndmask_b32_e32 v8, 0, v15, vcc
	v_add_f32_e32 v8, v7, v8
	v_pk_add_f32 v[0:1], v[0:1], v[8:9] op_sel_hi:[1,0]
	v_pk_add_f32 v[2:3], v[2:3], v[8:9] op_sel_hi:[1,0]
	s_and_b32 s10, s6, 0xf800
	ds_write_b128 v4, v[0:3]
	v_add_u32_e32 v0, s10, v96
	v_ashrrev_i32_e32 v1, 31, v0
	s_lshl_b32 s6, s8, 6
	v_lshlrev_b64 v[0:1], 9, v[0:1]
	s_and_b32 s11, s6, 0x1c0
	v_or_b32_e32 v0, s11, v0
	v_lshl_add_u64 v[88:89], v[0:1], 1, s[4:5]
	v_lshl_add_u64 v[0:1], v[88:89], 0, v[136:137]
	s_mov_b64 s[6:7], 0x30000000
	v_lshl_add_u64 v[2:3], v[0:1], 0, s[6:7]
	s_brev_b32 s6, 12
	v_add_co_u32_e32 v0, vcc, s6, v0
	s_waitcnt lgkmcnt(0)
	s_barrier
	v_addc_co_u32_e32 v1, vcc, 0, v1, vcc
	global_load_dwordx4 v[64:67], v[2:3], off offset:32
	global_load_dwordx4 v[68:71], v[2:3], off offset:64
	global_load_dwordx4 v[72:75], v[0:1], off
	global_load_dwordx4 v[76:79], v[2:3], off offset:96
	v_ashrrev_i32_e32 v0, 3, v6
	v_add_u32_e32 v2, s10, v0
	s_lshl_b32 s6, s9, 18
	v_ashrrev_i32_e32 v3, 31, v2
	s_add_u32 s6, s4, s6
	v_lshlrev_b64 v[2:3], 10, v[2:3]
	s_addc_u32 s7, s5, 0
	v_lshl_add_u64 v[2:3], s[4:5], 0, v[2:3]
	s_lshl_b32 s88, s11, 1
	v_lshlrev_b32_e32 v1, 4, v6
	v_lshl_add_u64 v[2:3], v[2:3], 0, s[88:89]
	v_and_b32_e32 v4, 0x70, v1
	v_mov_b32_e32 v5, v137
	v_ashrrev_i32_e32 v1, 31, v0
	v_lshl_add_u64 v[2:3], v[2:3], 0, v[4:5]
	v_lshlrev_b64 v[6:7], 12, v[0:1]
	s_brev_b32 s4, 36
	v_lshl_add_u64 v[6:7], s[6:7], 0, v[6:7]
	v_add_co_u32_e32 v8, vcc, s4, v2
	v_lshl_add_u64 v[6:7], v[6:7], 0, v[4:5]
	s_nop 0
	v_addc_co_u32_e32 v9, vcc, 0, v3, vcc
	s_brev_b32 s4, 44
	v_add_co_u32_e32 v10, vcc, s4, v6
	s_lshr_b32 s4, s8, 6
	s_nop 0
	v_addc_co_u32_e32 v11, vcc, 0, v7, vcc
	global_load_dwordx4 v[80:83], v[8:9], off
	global_load_dwordx4 v[84:87], v[10:11], off
	s_and_b32 s4, s4, 28
	s_sub_i32 s11, 32, s4
	s_mov_b64 s[4:5], 0x24000000
	v_lshl_add_u64 v[90:91], v[2:3], 0, s[4:5]
	s_mov_b64 s[4:5], 0x34000000
	v_lshlrev_b32_e32 v5, 2, v96
	v_lshl_add_u64 v[92:93], v[6:7], 0, s[4:5]
	s_movk_i32 s4, 0x90
	v_lshlrev_b32_e32 v1, 3, v16
	ds_read_b32 v97, v5
	v_mad_u64_u32 v[94:95], s[4:5], v0, s4, v[4:5]
	v_lshlrev_b32_e32 v95, 2, v16
	v_sub_u32_e32 v16, v136, v1
	v_mul_u32_u24_e32 v17, 0x90, v17
	v_cmp_lt_i32_e32 vcc, v177, v178
	v_mov_b32_e32 v14, v137
	v_mov_b32_e32 v15, v137
	v_cndmask_b32_e32 v0, v171, v177, vcc
	v_add_u32_e32 v16, v16, v17
	v_or_b32_e32 v98, 31, v12
	v_lshlrev_b32_e32 v99, 2, v0
	v_mov_b32_e32 v0, v137
	v_mov_b32_e32 v1, v137
	v_mov_b32_e32 v2, v137
	v_mov_b32_e32 v3, v137
	v_mov_b32_e32 v4, v137
	v_mov_b32_e32 v5, v137
	v_mov_b32_e32 v6, v137
	v_mov_b32_e32 v7, v137
	v_mov_b32_e32 v8, v137
	v_mov_b32_e32 v9, v137
	v_mov_b32_e32 v10, v137
	v_mov_b32_e32 v11, v137
	v_mov_b32_e32 v12, v137
	v_mov_b32_e32 v13, v137
	v_add_u32_e32 v101, v136, v17
	v_add_u32_e32 v102, 0x4000, v16
	v_add_u32_e32 v103, 0x5000, v16
	v_mov_b64_e32 v[30:31], v[14:15]
	s_mov_b32 s10, 0
	v_mov_b32_e32 v105, 0xf149f2ca
	s_mov_b64 s[4:5], 0
	v_mov_b32_e32 v104, v136
	v_mov_b64_e32 v[28:29], v[12:13]
	v_mov_b64_e32 v[26:27], v[10:11]
	v_mov_b64_e32 v[24:25], v[8:9]
	v_mov_b64_e32 v[22:23], v[6:7]
	v_mov_b64_e32 v[20:21], v[4:5]
	v_mov_b64_e32 v[18:19], v[2:3]
	v_mov_b64_e32 v[16:17], v[0:1]
	s_waitcnt lgkmcnt(0)
	v_mov_b32_e32 v144, v97
	v_mov_b32_e32 v145, v97
	v_mov_b32_e32 v146, v97
	v_mov_b32_e32 v147, v97
	v_mov_b32_e32 v148, v97
	v_mov_b32_e32 v149, v97
	v_mov_b32_e32 v150, v97
	v_mov_b32_e32 v151, v97
	v_mov_b32_e32 v152, v97
	v_mov_b32_e32 v153, v97
	v_mov_b32_e32 v154, v97
	v_mov_b32_e32 v155, v97
	v_mov_b32_e32 v156, v97
	v_mov_b32_e32 v157, v97
	v_mov_b32_e32 v158, v97
	v_mov_b32_e32 v159, v97
	v_readfirstlane_b32 s100, v98
	s_branch .LBB0_935

.LBB0_935:
	s_mov_b64 s[8:9], s[4:5]
	s_add_u32 s4, s8, 1
	s_addc_u32 s5, s9, 0
	s_cmp_ge_u32 s4, s11
	s_cselect_b64 s[6:7], -1, 0
	s_cmp_lt_u32 s4, s11
	s_cselect_b64 s[12:13], -1, 0
	v_cndmask_b32_e64 v32, 0, 1, s[12:13]
	v_mov_b32_e32 v33, s89
	v_lshl_add_u64 v[32:33], s[8:9], 0, v[32:33]
	v_lshlrev_b64 v[34:35], 16, v[32:33]
	v_lshl_add_u64 v[34:35], v[90:91], 0, v[34:35]
	v_lshlrev_b32_e32 v136, 6, v32
	s_waitcnt lgkmcnt(0)
	s_barrier
	s_waitcnt vmcnt(1)
	ds_write_b128 v94, v[80:83] offset:8192
	s_waitcnt vmcnt(0)
	ds_write_b128 v94, v[84:87] offset:17408
	s_waitcnt lgkmcnt(0)
	s_barrier
	v_lshl_add_u64 v[32:33], v[136:137], 1, v[92:93]
	global_load_dwordx4 v[80:83], v[34:35], off
	global_load_dwordx4 v[84:87], v[32:33], off
	v_cmp_le_i32_e32 vcc, s10, v98
	s_and_saveexec_b64 s[8:9], vcc
	s_cbranch_execz .LBB0_934
	s_add_i32 s101, s10, 94
	s_cmp_le_i32 s101, s100
	s_cbranch_scc1 .Latt_nomask
	ds_read_b128 v[32:35], v101 offset:8192
	ds_read_b128 v[36:39], v101 offset:8224
	v_add_u32_e32 v130, s10, v95
	v_cmp_le_i32_e32 vcc, v130, v96
	v_add_u32_e32 v131, 2, v130
	s_waitcnt lgkmcnt(1)
	v_mfma_f32_32x32x16_bf16 v[48:63], v[32:35], v[72:75], v[144:159]
	ds_read_b128 v[32:35], v101 offset:8256
	ds_read_b128 v[106:109], v101 offset:8288
	v_add_u32_e32 v132, 3, v130
	v_add_u32_e32 v133, 8, v130
	v_add_u32_e32 v134, 9, v130
	s_mov_b32 s12, 0xf149f2ca
	s_waitcnt lgkmcnt(2)
	v_mfma_f32_32x32x16_bf16 v[48:63], v[36:39], v[64:67], v[48:63]
	s_waitcnt lgkmcnt(1)
	v_mfma_f32_32x32x16_bf16 v[48:63], v[32:35], v[68:71], v[48:63]
	ds_read_b128 v[32:35], v101 offset:12800
	ds_read_b128 v[110:113], v101 offset:12832
	ds_read_b128 v[114:117], v101 offset:12864
	ds_read_b128 v[118:121], v101 offset:12896
	ds_read_b128 v[122:125], v104
	ds_read_b128 v[126:129], v104 offset:32
	s_waitcnt lgkmcnt(6)
	v_mfma_f32_32x32x16_bf16 v[48:63], v[106:109], v[76:79], v[48:63]
	s_waitcnt lgkmcnt(5)
	v_mfma_f32_32x32x16_bf16 v[32:47], v[32:35], v[72:75], v[144:159]
	s_nop 9
	s_waitcnt lgkmcnt(1)
	v_sub_f32_e32 v48, v48, v122
	v_sub_f32_e32 v49, v49, v123
	v_cndmask_b32_e32 v106, v187, v48, vcc
	v_cmp_lt_i32_e32 vcc, v130, v96
	v_sub_f32_e32 v50, v50, v124
	s_nop 0
	v_cndmask_b32_e32 v107, v187, v49, vcc
	v_cmp_le_i32_e32 vcc, v131, v96
	v_sub_f32_e32 v51, v51, v125
	s_nop 0
	v_cndmask_b32_e32 v108, v187, v50, vcc
	v_cmp_le_i32_e32 vcc, v132, v96
	s_waitcnt lgkmcnt(0)
	v_sub_f32_e32 v52, v52, v126
	v_cndmask_b32_e32 v109, v187, v51, vcc
	v_cmp_le_i32_e32 vcc, v133, v96
	v_sub_f32_e32 v53, v53, v127
	s_nop 0
	v_cndmask_b32_e32 v122, v187, v52, vcc
	v_cmp_le_i32_e32 vcc, v134, v96
	v_add_u32_e32 v50, 10, v130
	v_sub_f32_e32 v49, v54, v128
	v_cndmask_b32_e32 v123, v187, v53, vcc
	v_cmp_le_i32_e32 vcc, v50, v96
	v_max3_f32 v48, v106, s12, v107
	v_mfma_f32_32x32x16_bf16 v[32:47], v[110:113], v[64:67], v[32:47]
	v_cndmask_b32_e32 v110, v187, v49, vcc
	v_add_u32_e32 v50, 11, v130
	v_max3_f32 v48, v48, v108, v109
	v_sub_f32_e32 v49, v55, v129
	v_cmp_le_i32_e32 vcc, v50, v96
	v_max3_f32 v48, v48, v122, v123
	v_add_u32_e32 v113, 16, v130
	v_cndmask_b32_e32 v111, v187, v49, vcc
	v_max3_f32 v112, v48, v110, v111
	ds_read_b128 v[48:51], v104 offset:64
	ds_read_b128 v[52:55], v104 offset:96
	v_cmp_le_i32_e32 vcc, v113, v96
	v_mfma_f32_32x32x16_bf16 v[32:47], v[114:117], v[68:71], v[32:47]
	s_waitcnt lgkmcnt(1)
	v_sub_f32_e32 v48, v56, v48
	v_cndmask_b32_e32 v56, v187, v48, vcc
	v_sub_f32_e32 v48, v57, v49
	v_add_u32_e32 v49, 17, v130
	v_cmp_le_i32_e32 vcc, v49, v96
	v_sub_f32_e32 v49, v58, v50
	v_add_u32_e32 v50, 18, v130
	v_cndmask_b32_e32 v57, v187, v48, vcc
	v_cmp_le_i32_e32 vcc, v50, v96
	v_add_u32_e32 v50, 19, v130
	v_max3_f32 v48, v112, v56, v57
	v_cndmask_b32_e32 v58, v187, v49, vcc
	v_sub_f32_e32 v49, v59, v51
	v_cmp_le_i32_e32 vcc, v50, v96
	s_waitcnt lgkmcnt(0)
	v_sub_f32_e32 v50, v60, v52
	v_cndmask_b32_e32 v59, v187, v49, vcc
	v_add_u32_e32 v49, 24, v130
	v_cmp_le_i32_e32 vcc, v49, v96
	v_sub_f32_e32 v49, v61, v53
	s_nop 0
	v_cndmask_b32_e32 v60, v187, v50, vcc
	v_add_u32_e32 v50, 25, v130
	v_cmp_le_i32_e32 vcc, v50, v96
	v_max3_f32 v48, v48, v58, v59
	v_mfma_f32_32x32x16_bf16 v[32:47], v[118:121], v[76:79], v[32:47]
	v_cndmask_b32_e32 v61, v187, v49, vcc
	v_max3_f32 v52, v48, v60, v61
	v_add_u32_e32 v49, 26, v130
	v_sub_f32_e32 v48, v62, v54
	v_cmp_le_i32_e32 vcc, v49, v96
	v_add_u32_e32 v49, 27, v130
	v_add_u32_e32 v113, 32, v130
	v_cndmask_b32_e32 v62, v187, v48, vcc
	v_sub_f32_e32 v48, v63, v55
	v_cmp_le_i32_e32 vcc, v49, v96
	s_nop 1
	v_cndmask_b32_e32 v63, v187, v48, vcc
	ds_read_b128 v[48:51], v104 offset:128
	v_max3_f32 v112, v52, v62, v63
	ds_read_b128 v[52:55], v104 offset:160
	v_cmp_le_i32_e32 vcc, v113, v96
	v_add_u32_e32 v113, 48, v130
	s_waitcnt lgkmcnt(1)
	v_sub_f32_e32 v32, v32, v48
	v_cndmask_b32_e32 v48, v187, v32, vcc
	v_mov_b32_e32 v32, v33
	v_add_u32_e32 v33, 33, v130
	v_sub_f32_e32 v32, v32, v49
	v_cmp_le_i32_e32 vcc, v33, v96
	v_mov_b32_e32 v33, v34
	v_add_u32_e32 v34, 34, v130
	v_cndmask_b32_e32 v49, v187, v32, vcc
	v_sub_f32_e32 v33, v33, v50
	v_cmp_le_i32_e32 vcc, v34, v96
	v_add_u32_e32 v34, 35, v130
	v_max3_f32 v32, v112, v48, v49
	v_cndmask_b32_e32 v50, v187, v33, vcc
	v_sub_f32_e32 v33, v35, v51
	v_cmp_le_i32_e32 vcc, v34, v96
	s_waitcnt lgkmcnt(0)
	v_sub_f32_e32 v34, v36, v52
	v_cndmask_b32_e32 v51, v187, v33, vcc
	v_add_u32_e32 v33, 40, v130
	v_cmp_le_i32_e32 vcc, v33, v96
	v_sub_f32_e32 v33, v37, v53
	s_nop 0
	v_cndmask_b32_e32 v52, v187, v34, vcc
	v_add_u32_e32 v34, 41, v130
	v_cmp_le_i32_e32 vcc, v34, v96
	v_max3_f32 v32, v32, v50, v51
	s_nop 0
	v_cndmask_b32_e32 v53, v187, v33, vcc
	v_max3_f32 v36, v32, v52, v53
	v_add_u32_e32 v33, 42, v130
	v_sub_f32_e32 v32, v38, v54
	v_cmp_le_i32_e32 vcc, v33, v96
	v_add_u32_e32 v33, 43, v130
	s_nop 0
	v_cndmask_b32_e32 v54, v187, v32, vcc
	v_sub_f32_e32 v32, v39, v55
	v_cmp_le_i32_e32 vcc, v33, v96
	s_nop 1
	v_cndmask_b32_e32 v55, v187, v32, vcc
	ds_read_b128 v[32:35], v104 offset:192
	v_max3_f32 v112, v36, v54, v55
	ds_read_b128 v[36:39], v104 offset:224
	v_cmp_le_i32_e32 vcc, v113, v96
	s_waitcnt lgkmcnt(1)
	v_sub_f32_e32 v32, v40, v32
	v_sub_f32_e32 v33, v41, v33
	v_add_u32_e32 v40, 49, v130
	v_cndmask_b32_e32 v32, v187, v32, vcc
	v_cmp_le_i32_e32 vcc, v40, v96
	v_sub_f32_e32 v34, v42, v34
	v_add_u32_e32 v41, 50, v130
	v_cndmask_b32_e32 v33, v187, v33, vcc
	v_cmp_le_i32_e32 vcc, v41, v96
	v_sub_f32_e32 v35, v43, v35
	v_add_u32_e32 v41, 51, v130
	v_cndmask_b32_e32 v34, v187, v34, vcc
	v_cmp_le_i32_e32 vcc, v41, v96
	v_add_u32_e32 v41, 56, v130
	s_nop 0
	v_cndmask_b32_e32 v35, v187, v35, vcc
	v_cmp_le_i32_e32 vcc, v41, v96
	s_waitcnt lgkmcnt(0)
	v_sub_f32_e32 v36, v44, v36
	v_sub_f32_e32 v37, v45, v37
	v_add_u32_e32 v41, 57, v130
	v_max3_f32 v40, v112, v32, v33
	v_cndmask_b32_e32 v36, v187, v36, vcc
	v_cmp_le_i32_e32 vcc, v41, v96
	v_max3_f32 v40, v40, v34, v35
	s_nop 0
	v_cndmask_b32_e32 v112, v187, v37, vcc
	v_max3_f32 v37, v40, v36, v112
	v_sub_f32_e32 v38, v46, v38
	v_add_u32_e32 v40, 58, v130
	v_cmp_le_i32_e32 vcc, v40, v96
	s_nop 1
	v_cndmask_b32_e32 v46, v187, v38, vcc
	v_sub_f32_e32 v38, v47, v39
	v_add_u32_e32 v39, 59, v130
	v_cmp_le_i32_e32 vcc, v39, v96
	s_nop 1
	v_cndmask_b32_e32 v47, v187, v38, vcc
	v_max3_f32 v37, v37, v46, v47
	ds_bpermute_b32 v38, v99, v37
	s_waitcnt lgkmcnt(0)
	v_max3_f32 v113, v105, v37, v38
	s_mov_b32 s99, 0x3fb8aa3b
	v_mul_f32_e32 v250, 0xbfb8aa3b, v113
	v_fma_f32 v38, v106, s99, v250
	v_exp_f32_e32 v38, v38
	v_fma_f32 v39, v107, s99, v250
	v_exp_f32_e32 v39, v39
	v_fma_f32 v40, v108, s99, v250
	v_exp_f32_e32 v40, v40
	v_fma_f32 v41, v109, s99, v250
	v_exp_f32_e32 v41, v41
	v_fma_f32 v43, v122, s99, v250
	v_add_f32_e32 v42, 0, v38
	v_exp_f32_e32 v43, v43
	v_fma_f32 v44, v123, s99, v250
	v_sub_f32_e32 v37, v105, v113
	v_add_f32_e32 v42, v39, v42
	v_exp_f32_e32 v44, v44
	v_fma_f32 v45, v110, s99, v250
	v_add_f32_e32 v42, v40, v42
	v_exp_f32_e32 v45, v45
	v_fma_f32 v105, v111, s99, v250
	v_add_f32_e32 v42, v41, v42
	v_exp_f32_e32 v105, v105
	v_fma_f32 v56, v56, s99, v250
	v_add_f32_e32 v42, v43, v42
	v_exp_f32_e32 v56, v56
	v_fma_f32 v57, v57, s99, v250
	v_add_f32_e32 v42, v44, v42
	v_exp_f32_e32 v57, v57
	v_fma_f32 v58, v58, s99, v250
	v_add_f32_e32 v42, v45, v42
	v_exp_f32_e32 v58, v58
	v_fma_f32 v59, v59, s99, v250
	v_add_f32_e32 v42, v105, v42
	v_exp_f32_e32 v59, v59
	v_fma_f32 v60, v60, s99, v250
	v_add_f32_e32 v42, v56, v42
	v_exp_f32_e32 v60, v60
	v_fma_f32 v61, v61, s99, v250
	v_add_f32_e32 v42, v57, v42
	v_exp_f32_e32 v61, v61
	v_fma_f32 v62, v62, s99, v250
	v_add_f32_e32 v42, v58, v42
	v_exp_f32_e32 v62, v62
	v_fma_f32 v63, v63, s99, v250
	v_add_f32_e32 v42, v59, v42
	v_exp_f32_e32 v63, v63
	v_add_f32_e32 v42, v60, v42
	v_add_f32_e32 v42, v61, v42
	v_add_f32_e32 v42, v62, v42
	v_add_f32_e32 v106, v63, v42
	v_fma_f32 v42, v48, s99, v250
	v_exp_f32_e32 v48, v42
	v_fma_f32 v32, v32, s99, v250
	v_fma_f32 v42, v49, s99, v250
	v_exp_f32_e32 v107, v32
	v_exp_f32_e32 v49, v42
	v_fma_f32 v32, v33, s99, v250
	v_fma_f32 v42, v50, s99, v250
	v_exp_f32_e32 v33, v32
	v_exp_f32_e32 v50, v42
	v_fma_f32 v32, v34, s99, v250
	v_fma_f32 v42, v51, s99, v250
	v_exp_f32_e32 v108, v32
	v_mul_f32_e32 v37, 0x3fb8aa3b, v37
	v_exp_f32_e32 v51, v42
	v_fma_f32 v32, v35, s99, v250
	v_fma_f32 v34, v36, s99, v250
	v_fma_f32 v42, v52, s99, v250
	v_exp_f32_e32 v109, v32
	v_exp_f32_e32 v32, v37
	v_exp_f32_e32 v110, v34
	ds_read2_b64 v[34:37], v102 offset0:128 offset1:130
	v_exp_f32_e32 v52, v42
	v_fma_f32 v42, v53, s99, v250
	v_exp_f32_e32 v53, v42
	v_fma_f32 v42, v54, s99, v250
	v_exp_f32_e32 v54, v42
	v_fma_f32 v42, v55, s99, v250
	v_exp_f32_e32 v55, v42
	v_cvt_pk_bf16_f32 v38, v38, v39
	v_cvt_pk_bf16_f32 v39, v40, v41
	v_cvt_pk_bf16_f32 v40, v43, v44
	v_cvt_pk_bf16_f32 v41, v45, v105
	ds_read2_b64 v[42:45], v103 offset0:192 offset1:194
	v_pk_mul_f32 v[30:31], v[30:31], v[32:33] op_sel_hi:[1,0]
	v_pk_mul_f32 v[28:29], v[28:29], v[32:33] op_sel_hi:[1,0]
	v_pk_mul_f32 v[26:27], v[26:27], v[32:33] op_sel_hi:[1,0]
	v_pk_mul_f32 v[24:25], v[24:25], v[32:33] op_sel_hi:[1,0]
	v_pk_mul_f32 v[22:23], v[22:23], v[32:33] op_sel_hi:[1,0]
	v_pk_mul_f32 v[20:21], v[20:21], v[32:33] op_sel_hi:[1,0]
	v_pk_mul_f32 v[18:19], v[18:19], v[32:33] op_sel_hi:[1,0]
	v_pk_mul_f32 v[16:17], v[16:17], v[32:33] op_sel_hi:[1,0]
	v_pk_mul_f32 v[14:15], v[14:15], v[32:33] op_sel_hi:[1,0]
	v_pk_mul_f32 v[12:13], v[12:13], v[32:33] op_sel_hi:[1,0]
	s_waitcnt lgkmcnt(1)
	v_mfma_f32_32x32x16_bf16 v[16:31], v[34:37], v[38:41], v[16:31]
	ds_read2_b64 v[34:37], v102 offset0:132 offset1:134
	v_mul_f32_e64 v10, v10, v32
	v_mul_f32_e64 v11, v11, v32
	v_mul_f32_e64 v8, v8, v32
	v_mul_f32_e64 v9, v9, v32
	v_pk_mul_f32 v[6:7], v[6:7], v[32:33] op_sel_hi:[1,0]
	v_pk_mul_f32 v[4:5], v[4:5], v[32:33] op_sel_hi:[1,0]
	v_pk_mul_f32 v[2:3], v[2:3], v[32:33] op_sel_hi:[1,0]
	v_pk_mul_f32 v[0:1], v[0:1], v[32:33] op_sel_hi:[1,0]
	s_waitcnt lgkmcnt(1)
	s_nop 0
	v_mfma_f32_32x32x16_bf16 v[0:15], v[42:45], v[38:41], v[0:15]
	v_fma_f32 v105, v112, s99, v250
	v_cvt_pk_bf16_f32 v38, v56, v57
	v_cvt_pk_bf16_f32 v39, v58, v59
	v_cvt_pk_bf16_f32 v40, v60, v61
	v_cvt_pk_bf16_f32 v41, v62, v63
	ds_read2_b64 v[42:45], v103 offset0:196 offset1:198
	v_add_f32_e32 v57, v48, v106
	s_waitcnt lgkmcnt(1)
	v_mfma_f32_32x32x16_bf16 v[16:31], v[34:37], v[38:41], v[16:31]
	v_fma_f32 v34, v46, s99, v250
	v_exp_f32_e32 v46, v34
	v_fma_f32 v47, v47, s99, v250
	ds_read2_b64 v[34:37], v102 offset0:136 offset1:138
	v_exp_f32_e32 v56, v105
	s_waitcnt lgkmcnt(1)
	v_mfma_f32_32x32x16_bf16 v[0:15], v[42:45], v[38:41], v[0:15]
	ds_read2_b64 v[42:45], v103 offset0:200 offset1:202
	v_cvt_pk_bf16_f32 v38, v48, v49
	v_cvt_pk_bf16_f32 v39, v50, v51
	v_cvt_pk_bf16_f32 v40, v52, v53
	v_cvt_pk_bf16_f32 v41, v54, v55
	v_exp_f32_e32 v47, v47
	v_mov_b32_e32 v105, v113
	s_waitcnt lgkmcnt(1)
	v_mfma_f32_32x32x16_bf16 v[16:31], v[34:37], v[38:41], v[16:31]
	v_add_f32_e32 v34, v49, v57
	v_add_f32_e32 v34, v50, v34
	v_add_f32_e32 v34, v51, v34
	v_add_f32_e32 v34, v52, v34
	v_add_f32_e32 v34, v53, v34
	v_add_f32_e32 v48, v54, v34
	ds_read2_b64 v[34:37], v102 offset0:140 offset1:142
	s_waitcnt lgkmcnt(1)
	v_mfma_f32_32x32x16_bf16 v[0:15], v[42:45], v[38:41], v[0:15]
	ds_read2_b64 v[42:45], v103 offset0:204 offset1:206
	v_add_f32_e32 v38, v55, v48
	v_add_f32_e32 v48, v107, v38
	v_cvt_pk_bf16_f32 v38, v107, v33
	v_cvt_pk_bf16_f32 v39, v108, v109
	v_cvt_pk_bf16_f32 v40, v110, v56
	v_cvt_pk_bf16_f32 v41, v46, v47
	v_add_f32_e32 v33, v33, v48
	v_add_f32_e32 v33, v108, v33
	s_waitcnt lgkmcnt(1)
	v_mfma_f32_32x32x16_bf16 v[16:31], v[34:37], v[38:41], v[16:31]
	v_add_f32_e32 v33, v109, v33
	v_add_f32_e32 v33, v110, v33
	v_add_f32_e32 v33, v56, v33
	v_add_f32_e32 v33, v46, v33
	v_add_f32_e32 v33, v47, v33
	v_fmac_f32_e32 v33, v100, v32
	v_mov_b32_e32 v100, v33
	s_waitcnt lgkmcnt(0)
	v_mfma_f32_32x32x16_bf16 v[0:15], v[42:45], v[38:41], v[0:15]
	s_branch .LBB0_934
.Latt_nomask:
	ds_read_b128 v[32:35], v101 offset:8192
	ds_read_b128 v[36:39], v101 offset:8224
	s_waitcnt lgkmcnt(1)
	v_mfma_f32_32x32x16_bf16 v[48:63], v[32:35], v[72:75], v[144:159]
	ds_read_b128 v[32:35], v101 offset:8256
	ds_read_b128 v[106:109], v101 offset:8288
	s_mov_b32 s12, 0xf149f2ca
	s_waitcnt lgkmcnt(2)
	v_mfma_f32_32x32x16_bf16 v[48:63], v[36:39], v[64:67], v[48:63]
	s_waitcnt lgkmcnt(1)
	v_mfma_f32_32x32x16_bf16 v[48:63], v[32:35], v[68:71], v[48:63]
	ds_read_b128 v[32:35], v101 offset:12800
	ds_read_b128 v[110:113], v101 offset:12832
	ds_read_b128 v[114:117], v101 offset:12864
	ds_read_b128 v[118:121], v101 offset:12896
	ds_read_b128 v[122:125], v104
	ds_read_b128 v[126:129], v104 offset:32
	s_waitcnt lgkmcnt(6)
	v_mfma_f32_32x32x16_bf16 v[48:63], v[106:109], v[76:79], v[48:63]
	s_waitcnt lgkmcnt(5)
	v_mfma_f32_32x32x16_bf16 v[32:47], v[32:35], v[72:75], v[144:159]
	s_nop 9
	s_waitcnt lgkmcnt(1)
	v_sub_f32_e32 v106, v48, v122
	v_sub_f32_e32 v107, v49, v123
	v_sub_f32_e32 v108, v50, v124
	v_sub_f32_e32 v109, v51, v125
	s_waitcnt lgkmcnt(0)
	v_sub_f32_e32 v122, v52, v126
	v_sub_f32_e32 v123, v53, v127
	v_sub_f32_e32 v49, v54, v128
	v_max3_f32 v48, v106, s12, v107
	v_mfma_f32_32x32x16_bf16 v[32:47], v[110:113], v[64:67], v[32:47]
	v_mov_b32_e32 v110, v49
	v_max3_f32 v48, v48, v108, v109
	v_sub_f32_e32 v111, v55, v129
	v_max3_f32 v48, v48, v122, v123
	v_max3_f32 v112, v48, v110, v111
	ds_read_b128 v[48:51], v104 offset:64
	ds_read_b128 v[52:55], v104 offset:96
	v_mfma_f32_32x32x16_bf16 v[32:47], v[114:117], v[68:71], v[32:47]
	s_waitcnt lgkmcnt(1)
	v_sub_f32_e32 v56, v56, v48
	v_sub_f32_e32 v57, v57, v49
	v_sub_f32_e32 v58, v58, v50
	v_max3_f32 v48, v112, v56, v57
	v_sub_f32_e32 v59, v59, v51
	s_waitcnt lgkmcnt(0)
	v_sub_f32_e32 v60, v60, v52
	v_sub_f32_e32 v61, v61, v53
	v_max3_f32 v48, v48, v58, v59
	v_mfma_f32_32x32x16_bf16 v[32:47], v[118:121], v[76:79], v[32:47]
	v_max3_f32 v52, v48, v60, v61
	v_sub_f32_e32 v62, v62, v54
	v_sub_f32_e32 v63, v63, v55
	s_nop 6
	ds_read_b128 v[48:51], v104 offset:128
	v_max3_f32 v112, v52, v62, v63
	ds_read_b128 v[52:55], v104 offset:160
	s_waitcnt lgkmcnt(1)
	v_sub_f32_e32 v48, v32, v48
	v_sub_f32_e32 v49, v33, v49
	v_sub_f32_e32 v50, v34, v50
	v_max3_f32 v32, v112, v48, v49
	v_sub_f32_e32 v51, v35, v51
	s_waitcnt lgkmcnt(0)
	v_sub_f32_e32 v52, v36, v52
	v_sub_f32_e32 v53, v37, v53
	v_max3_f32 v32, v32, v50, v51
	s_nop 0
	v_max3_f32 v36, v32, v52, v53
	v_sub_f32_e32 v54, v38, v54
	s_nop 0
	v_sub_f32_e32 v55, v39, v55
	s_nop 1
	ds_read_b128 v[32:35], v104 offset:192
	v_max3_f32 v112, v36, v54, v55
	ds_read_b128 v[36:39], v104 offset:224
	s_waitcnt lgkmcnt(1)
	v_sub_f32_e32 v32, v40, v32
	v_sub_f32_e32 v33, v41, v33
	v_sub_f32_e32 v34, v42, v34
	v_sub_f32_e32 v35, v43, v35
	s_waitcnt lgkmcnt(0)
	v_sub_f32_e32 v36, v44, v36
	v_sub_f32_e32 v37, v45, v37
	v_max3_f32 v40, v112, v32, v33
	v_max3_f32 v40, v40, v34, v35
	s_nop 0
	v_mov_b32_e32 v112, v37
	v_max3_f32 v37, v40, v36, v112
	v_sub_f32_e32 v46, v46, v38
	s_nop 1
	v_sub_f32_e32 v47, v47, v39
	s_nop 1
	v_max3_f32 v37, v37, v46, v47
	ds_bpermute_b32 v38, v99, v37
	s_waitcnt lgkmcnt(0)
	v_max3_f32 v113, v105, v37, v38
	s_mov_b32 s99, 0x3fb8aa3b
	v_mul_f32_e32 v250, 0xbfb8aa3b, v113
	v_fma_f32 v38, v106, s99, v250
	v_exp_f32_e32 v38, v38
	v_fma_f32 v39, v107, s99, v250
	v_exp_f32_e32 v39, v39
	v_fma_f32 v40, v108, s99, v250
	v_exp_f32_e32 v40, v40
	v_fma_f32 v41, v109, s99, v250
	v_exp_f32_e32 v41, v41
	v_fma_f32 v43, v122, s99, v250
	v_add_f32_e32 v42, 0, v38
	v_exp_f32_e32 v43, v43
	v_fma_f32 v44, v123, s99, v250
	v_sub_f32_e32 v37, v105, v113
	v_add_f32_e32 v42, v39, v42
	v_exp_f32_e32 v44, v44
	v_fma_f32 v45, v110, s99, v250
	v_add_f32_e32 v42, v40, v42
	v_exp_f32_e32 v45, v45
	v_fma_f32 v105, v111, s99, v250
	v_add_f32_e32 v42, v41, v42
	v_exp_f32_e32 v105, v105
	v_fma_f32 v56, v56, s99, v250
	v_add_f32_e32 v42, v43, v42
	v_exp_f32_e32 v56, v56
	v_fma_f32 v57, v57, s99, v250
	v_add_f32_e32 v42, v44, v42
	v_exp_f32_e32 v57, v57
	v_fma_f32 v58, v58, s99, v250
	v_add_f32_e32 v42, v45, v42
	v_exp_f32_e32 v58, v58
	v_fma_f32 v59, v59, s99, v250
	v_add_f32_e32 v42, v105, v42
	v_exp_f32_e32 v59, v59
	v_fma_f32 v60, v60, s99, v250
	v_add_f32_e32 v42, v56, v42
	v_exp_f32_e32 v60, v60
	v_fma_f32 v61, v61, s99, v250
	v_add_f32_e32 v42, v57, v42
	v_exp_f32_e32 v61, v61
	v_fma_f32 v62, v62, s99, v250
	v_add_f32_e32 v42, v58, v42
	v_exp_f32_e32 v62, v62
	v_fma_f32 v63, v63, s99, v250
	v_add_f32_e32 v42, v59, v42
	v_exp_f32_e32 v63, v63
	v_add_f32_e32 v42, v60, v42
	v_add_f32_e32 v42, v61, v42
	v_add_f32_e32 v42, v62, v42
	v_add_f32_e32 v106, v63, v42
	v_fma_f32 v42, v48, s99, v250
	v_exp_f32_e32 v48, v42
	v_fma_f32 v32, v32, s99, v250
	v_fma_f32 v42, v49, s99, v250
	v_exp_f32_e32 v107, v32
	v_exp_f32_e32 v49, v42
	v_fma_f32 v32, v33, s99, v250
	v_fma_f32 v42, v50, s99, v250
	v_exp_f32_e32 v33, v32
	v_exp_f32_e32 v50, v42
	v_fma_f32 v32, v34, s99, v250
	v_fma_f32 v42, v51, s99, v250
	v_exp_f32_e32 v108, v32
	v_mul_f32_e32 v37, 0x3fb8aa3b, v37
	v_exp_f32_e32 v51, v42
	v_fma_f32 v32, v35, s99, v250
	v_fma_f32 v34, v36, s99, v250
	v_fma_f32 v42, v52, s99, v250
	v_exp_f32_e32 v109, v32
	v_exp_f32_e32 v32, v37
	v_exp_f32_e32 v110, v34
	ds_read2_b64 v[34:37], v102 offset0:128 offset1:130
	v_exp_f32_e32 v52, v42
	v_fma_f32 v42, v53, s99, v250
	v_exp_f32_e32 v53, v42
	v_fma_f32 v42, v54, s99, v250
	v_exp_f32_e32 v54, v42
	v_fma_f32 v42, v55, s99, v250
	v_exp_f32_e32 v55, v42
	v_cvt_pk_bf16_f32 v38, v38, v39
	v_cvt_pk_bf16_f32 v39, v40, v41
	v_cvt_pk_bf16_f32 v40, v43, v44
	v_cvt_pk_bf16_f32 v41, v45, v105
	ds_read2_b64 v[42:45], v103 offset0:192 offset1:194
	v_pk_mul_f32 v[30:31], v[30:31], v[32:33] op_sel_hi:[1,0]
	v_pk_mul_f32 v[28:29], v[28:29], v[32:33] op_sel_hi:[1,0]
	v_pk_mul_f32 v[26:27], v[26:27], v[32:33] op_sel_hi:[1,0]
	v_pk_mul_f32 v[24:25], v[24:25], v[32:33] op_sel_hi:[1,0]
	v_pk_mul_f32 v[22:23], v[22:23], v[32:33] op_sel_hi:[1,0]
	v_pk_mul_f32 v[20:21], v[20:21], v[32:33] op_sel_hi:[1,0]
	v_pk_mul_f32 v[18:19], v[18:19], v[32:33] op_sel_hi:[1,0]
	v_pk_mul_f32 v[16:17], v[16:17], v[32:33] op_sel_hi:[1,0]
	v_pk_mul_f32 v[14:15], v[14:15], v[32:33] op_sel_hi:[1,0]
	v_pk_mul_f32 v[12:13], v[12:13], v[32:33] op_sel_hi:[1,0]
	s_waitcnt lgkmcnt(1)
	v_mfma_f32_32x32x16_bf16 v[16:31], v[34:37], v[38:41], v[16:31]
	ds_read2_b64 v[34:37], v102 offset0:132 offset1:134
	v_mul_f32_e64 v10, v10, v32
	v_mul_f32_e64 v11, v11, v32
	v_mul_f32_e64 v8, v8, v32
	v_mul_f32_e64 v9, v9, v32
	v_pk_mul_f32 v[6:7], v[6:7], v[32:33] op_sel_hi:[1,0]
	v_pk_mul_f32 v[4:5], v[4:5], v[32:33] op_sel_hi:[1,0]
	v_pk_mul_f32 v[2:3], v[2:3], v[32:33] op_sel_hi:[1,0]
	v_pk_mul_f32 v[0:1], v[0:1], v[32:33] op_sel_hi:[1,0]
	s_waitcnt lgkmcnt(1)
	s_nop 0
	v_mfma_f32_32x32x16_bf16 v[0:15], v[42:45], v[38:41], v[0:15]
	v_fma_f32 v105, v112, s99, v250
	v_cvt_pk_bf16_f32 v38, v56, v57
	v_cvt_pk_bf16_f32 v39, v58, v59
	v_cvt_pk_bf16_f32 v40, v60, v61
	v_cvt_pk_bf16_f32 v41, v62, v63
	ds_read2_b64 v[42:45], v103 offset0:196 offset1:198
	v_add_f32_e32 v57, v48, v106
	s_waitcnt lgkmcnt(1)
	v_mfma_f32_32x32x16_bf16 v[16:31], v[34:37], v[38:41], v[16:31]
	v_fma_f32 v34, v46, s99, v250
	v_exp_f32_e32 v46, v34
	v_fma_f32 v47, v47, s99, v250
	ds_read2_b64 v[34:37], v102 offset0:136 offset1:138
	v_exp_f32_e32 v56, v105
	s_waitcnt lgkmcnt(1)
	v_mfma_f32_32x32x16_bf16 v[0:15], v[42:45], v[38:41], v[0:15]
	ds_read2_b64 v[42:45], v103 offset0:200 offset1:202
	v_cvt_pk_bf16_f32 v38, v48, v49
	v_cvt_pk_bf16_f32 v39, v50, v51
	v_cvt_pk_bf16_f32 v40, v52, v53
	v_cvt_pk_bf16_f32 v41, v54, v55
	v_exp_f32_e32 v47, v47
	v_mov_b32_e32 v105, v113
	s_waitcnt lgkmcnt(1)
	v_mfma_f32_32x32x16_bf16 v[16:31], v[34:37], v[38:41], v[16:31]
	v_add_f32_e32 v34, v49, v57
	v_add_f32_e32 v34, v50, v34
	v_add_f32_e32 v34, v51, v34
	v_add_f32_e32 v34, v52, v34
	v_add_f32_e32 v34, v53, v34
	v_add_f32_e32 v48, v54, v34
	ds_read2_b64 v[34:37], v102 offset0:140 offset1:142
	s_waitcnt lgkmcnt(1)
	v_mfma_f32_32x32x16_bf16 v[0:15], v[42:45], v[38:41], v[0:15]
	ds_read2_b64 v[42:45], v103 offset0:204 offset1:206
	v_add_f32_e32 v38, v55, v48
	v_add_f32_e32 v48, v107, v38
	v_cvt_pk_bf16_f32 v38, v107, v33
	v_cvt_pk_bf16_f32 v39, v108, v109
	v_cvt_pk_bf16_f32 v40, v110, v56
	v_cvt_pk_bf16_f32 v41, v46, v47
	v_add_f32_e32 v33, v33, v48
	v_add_f32_e32 v33, v108, v33
	s_waitcnt lgkmcnt(1)
	v_mfma_f32_32x32x16_bf16 v[16:31], v[34:37], v[38:41], v[16:31]
	v_add_f32_e32 v33, v109, v33
	v_add_f32_e32 v33, v110, v33
	v_add_f32_e32 v33, v56, v33
	v_add_f32_e32 v33, v46, v33
	v_add_f32_e32 v33, v47, v33
	v_fmac_f32_e32 v33, v100, v32
	v_mov_b32_e32 v100, v33
	s_waitcnt lgkmcnt(0)
	v_mfma_f32_32x32x16_bf16 v[0:15], v[42:45], v[38:41], v[0:15]
	s_branch .LBB0_934
